# work queues: a block gives up after 3 queue visits instead of 8, all four queue-driven phases
# speedup vs baseline: 1.0045x; 1.0045x over previous
.LBB0_198:
	s_or_b64 exec, exec, s[4:5]
	s_waitcnt lgkmcnt(0)
	s_barrier
	ds_read_b32 v0, v103
	s_movk_i32 s4, 0x1b0
	s_waitcnt lgkmcnt(0)
	v_cmp_gt_i32_e32 vcc, s4, v0
	v_readfirstlane_b32 s6, v0
	s_mov_b64 s[4:5], 0
	s_cbranch_vccnz .LBB0_201
	s_cmp_gt_i32 s47, 1
	s_cbranch_scc1 .LBB0_202
	s_add_i32 s4, s37, 1
	s_and_b32 s37, s4, 7
	s_add_i32 s47, s47, 1
	s_cbranch_execnz .LBB0_194
	s_branch .LBB0_203

.LBB0_610:
	s_or_b64 exec, exec, s[28:29]
	s_waitcnt lgkmcnt(0)
	s_barrier
	ds_read_b32 v0, v220
	s_movk_i32 s28, 0x120
	s_waitcnt lgkmcnt(0)
	v_cmp_gt_i32_e32 vcc, s28, v0
	v_readfirstlane_b32 s30, v0
	s_mov_b64 s[28:29], 0
	s_cbranch_vccnz .LBB0_613
	s_cmp_gt_i32 s63, 1
	s_cbranch_scc1 .LBB0_614
	s_add_i32 s28, s52, 1
	s_and_b32 s52, s28, 7
	s_add_i32 s63, s63, 1
	s_cbranch_execnz .LBB0_606
	s_branch .LBB0_615

.LBB0_814:
	s_or_b64 exec, exec, s[2:3]
	s_waitcnt lgkmcnt(0)
	s_barrier
	ds_read_b32 v0, v178
	s_movk_i32 s2, 0x100
	s_waitcnt lgkmcnt(0)
	v_cmp_gt_i32_e32 vcc, s2, v0
	v_readfirstlane_b32 s33, v0
	s_mov_b64 s[2:3], 0
	s_cbranch_vccnz .LBB0_817
	v_readlane_b32 s33, v248, 10
	s_cmp_gt_i32 s33, 1
	s_cbranch_scc1 .LBB0_818
	v_readlane_b32 s2, v248, 8
	s_add_i32 s2, s2, 1
	s_and_b32 s2, s2, 7
	v_writelane_b32 v248, s2, 8
	s_mov_b64 s[2:3], -1
	s_branch .LBB0_819

.LBB0_896:
	s_or_b64 exec, exec, s[8:9]
	s_waitcnt lgkmcnt(0)
	s_barrier
	ds_read_b32 v0, v105
	s_mov_b64 s[8:9], 0
	s_waitcnt lgkmcnt(0)
	v_cmp_gt_i32_e32 vcc, s15, v0
	v_readfirstlane_b32 s0, v0
	s_cbranch_vccnz .LBB0_899
	s_cmp_gt_i32 s20, 1
	s_cbranch_scc1 .LBB0_900
	s_add_i32 s0, s14, 1
	s_and_b32 s14, s0, 7
	s_add_i32 s20, s20, 1
	s_cbranch_execnz .LBB0_892
	s_branch .LBB0_901
